# GEMM2 fused epilogue: X1B/H stores as full 128B lines (w_out row reorder + DPP lane-pair exchange), on top of P6/P7 full-line stores
# speedup vs baseline: 1.0950x; 1.0023x over previous
; __device__ __forceinline__ unsigned cvt_pk_bf16(float lo, float hi) { unsigned r; asm("v_cvt_pk_bf16_f32 %0, %1, %2" : "=v"(r) : "v"(lo), "v"(hi)); return r; }
; template <bool PERMW, bool PERM32>
; __device__ __forceinline__ void transpose_cvt(const float* __restrict__ src, bf16_t* __restrict__ dst, int K, int N, float* T, int& tile_ctr, int blk, int nblk) {
;     ...
;     for (int tl = tl0; tl < ntiles; tl += nblk) {
;         const int k0 = (tl % nkt) * 64, n0 = (tl / nkt) * 256;
;         { const int n4 = (tid & 63) * 4, sc = PERMW ? win_src_col(n0 + n4) : n0 + n4; f32x4 v[8];
; #pragma unroll
;           for (int i = 0; i < 8; ++i) { const int k = (tid >> 6) + 8 * i; v[i] = *(const f32x4*)(src + (size_t)(k0 + k) * N + sc); }
; #pragma unroll
;           for (int i = 0; i < 8; ++i) { const int k = (tid >> 6) + 8 * i; *(f32x4*)(T + k * 256 + (n4 ^ (((k >> 3) & 7) << 2))) = v[i]; } }
;         __syncthreads();
; #pragma unroll
;         for (int i = 0; i < 4; ++i) { const int pi = tid + 512 * i, q = pi & 7, nl = pi >> 3, x = PERM32 ? (nl & ~31) + perm32(nl & 31) : nl; const float* tp = T + (8 * q) * 256 + (x ^ (q << 2)); uint4 o;
;             o.x = cvt_pk_bf16(tp[0], tp[256]); o.y = cvt_pk_bf16(tp[512], tp[768]); o.z = cvt_pk_bf16(tp[1024], tp[1280]); o.w = cvt_pk_bf16(tp[1536], tp[1792]);
;             *(uint4*)(dst + (size_t)(n0 + nl) * K + k0 + 8 * q) = o; }
;         __syncthreads();
.LBB0_33:
	s_ashr_i32 s14, s69, 31
	s_lshr_b32 s14, s14, 28
	s_add_i32 s14, s69, s14
	s_ashr_i32 s14, s14, 4
	s_lshl_b32 s72, s14, 10
	s_lshl_b32 s15, s14, 8
	s_sub_i32 s14, s70, s72
	v_add_u32_e32 v24, s14, v6
	v_or_b32_e32 v22, s15, v1
	v_add_u32_e32 v26, 8, v24
	v_add_u32_e32 v28, 16, v24
	v_add_u32_e32 v30, 24, v24
	v_add_u32_e32 v32, 32, v24
	v_add_u32_e32 v34, 40, v24
	v_add_u32_e32 v36, 48, v24
	v_add_u32_e32 v38, 56, v24
	v_ashrrev_i32_e32 v23, 31, v22
	v_ashrrev_i32_e32 v25, 31, v24
	v_ashrrev_i32_e32 v27, 31, v26
	v_ashrrev_i32_e32 v29, 31, v28
	v_ashrrev_i32_e32 v31, 31, v30
	v_ashrrev_i32_e32 v33, 31, v32
	v_ashrrev_i32_e32 v35, 31, v34
	v_ashrrev_i32_e32 v37, 31, v36
	v_ashrrev_i32_e32 v39, 31, v38
	v_lshl_add_u64 v[22:23], v[22:23], 2, s[26:27]
	v_lshlrev_b64 v[24:25], 12, v[24:25]
	v_lshlrev_b64 v[26:27], 12, v[26:27]
	v_lshlrev_b64 v[28:29], 12, v[28:29]
	v_lshlrev_b64 v[30:31], 12, v[30:31]
	v_lshlrev_b64 v[32:33], 12, v[32:33]
	v_lshlrev_b64 v[34:35], 12, v[34:35]
	v_lshlrev_b64 v[36:37], 12, v[36:37]
	v_lshlrev_b64 v[38:39], 12, v[38:39]
	v_lshl_add_u64 v[24:25], v[22:23], 0, v[24:25]
	v_lshl_add_u64 v[26:27], v[22:23], 0, v[26:27]
	v_lshl_add_u64 v[40:41], v[22:23], 0, v[28:29]
	v_lshl_add_u64 v[42:43], v[22:23], 0, v[30:31]
	v_lshl_add_u64 v[44:45], v[22:23], 0, v[32:33]
	v_lshl_add_u64 v[46:47], v[22:23], 0, v[34:35]
	v_lshl_add_u64 v[48:49], v[22:23], 0, v[36:37]
	v_lshl_add_u64 v[50:51], v[22:23], 0, v[38:39]
	global_load_dwordx4 v[22:25], v[24:25], off nt
	s_nop 0
	global_load_dwordx4 v[26:29], v[26:27], off nt
	s_nop 0
	global_load_dwordx4 v[30:33], v[40:41], off nt
	global_load_dwordx4 v[34:37], v[42:43], off nt
	s_nop 0
	global_load_dwordx4 v[38:41], v[44:45], off nt
	s_nop 0
	global_load_dwordx4 v[42:45], v[46:47], off nt
	s_nop 0
	global_load_dwordx4 v[46:49], v[48:49], off nt
	s_nop 0
	global_load_dwordx4 v[50:53], v[50:51], off nt
	v_lshrrev_b32_e32 v56, 5, v2
	v_lshl_add_u32 v54, v56, 6, v2
	v_lshl_add_u32 v54, v56, 5, v54
	v_add_u32_e32 v54, s15, v54
	v_add_u32_e32 v56, 32, v54
	v_add_u32_e32 v58, 64, v54
	v_add_u32_e32 v60, 0x60, v54
	s_ashr_i32 s15, s14, 31
	v_ashrrev_i32_e32 v55, 31, v54
	s_add_i32 s69, s69, s33
	s_add_i32 s70, s70, s71
	v_ashrrev_i32_e32 v57, 31, v56
	v_ashrrev_i32_e32 v59, 31, v58
	v_ashrrev_i32_e32 v61, 31, v60
	v_lshl_add_u64 v[62:63], s[14:15], 1, v[4:5]
	v_lshlrev_b64 v[54:55], 11, v[54:55]
	v_lshlrev_b64 v[56:57], 11, v[56:57]
	v_lshlrev_b64 v[58:59], 11, v[58:59]
	v_lshlrev_b64 v[60:61], 11, v[60:61]
	s_cmp_lt_i32 s69, 64
	v_lshl_add_u64 v[54:55], v[62:63], 0, v[54:55]
	v_lshl_add_u64 v[56:57], v[62:63], 0, v[56:57]
	v_lshl_add_u64 v[58:59], v[62:63], 0, v[58:59]
	v_lshl_add_u64 v[60:61], v[62:63], 0, v[60:61]
	s_waitcnt vmcnt(7)
	ds_write_b128 v8, v[22:25]
	s_waitcnt vmcnt(6)
	ds_write_b128 v9, v[26:29]
	s_waitcnt vmcnt(5)
	ds_write_b128 v10, v[30:33]
	s_waitcnt vmcnt(4)
	ds_write_b128 v11, v[34:37]
	s_waitcnt vmcnt(3)
	ds_write_b128 v12, v[38:41]
	s_waitcnt vmcnt(2)
	ds_write_b128 v13, v[42:45]
	s_waitcnt vmcnt(1)
	ds_write_b128 v14, v[46:49]
	s_waitcnt vmcnt(0)
	ds_write_b128 v15, v[50:53]
	s_waitcnt lgkmcnt(0)
	s_barrier
	ds_read2st64_b32 v[22:23], v7 offset1:4
	ds_read2st64_b32 v[24:25], v7 offset0:8 offset1:12
	ds_read2st64_b32 v[26:27], v7 offset0:16 offset1:20
	ds_read2st64_b32 v[28:29], v7 offset0:24 offset1:28
	ds_read2st64_b32 v[30:31], v17 offset1:4
	ds_read2st64_b32 v[32:33], v17 offset0:8 offset1:12
	ds_read2st64_b32 v[34:35], v17 offset0:16 offset1:20
	ds_read2st64_b32 v[36:37], v17 offset0:24 offset1:28
	ds_read2st64_b32 v[38:39], v19 offset1:4
	ds_read2st64_b32 v[40:41], v19 offset0:8 offset1:12
	ds_read2st64_b32 v[42:43], v19 offset0:16 offset1:20
	ds_read2st64_b32 v[44:45], v19 offset0:24 offset1:28
	ds_read2st64_b32 v[46:47], v21 offset1:4
	ds_read2st64_b32 v[48:49], v21 offset0:8 offset1:12
	ds_read2st64_b32 v[50:51], v21 offset0:16 offset1:20
	ds_read2st64_b32 v[52:53], v21 offset0:24 offset1:28
	s_waitcnt lgkmcnt(14)
	v_cvt_pk_bf16_f32 v22, v22, v23
	v_cvt_pk_bf16_f32 v23, v24, v25
	s_waitcnt lgkmcnt(13)
	v_cvt_pk_bf16_f32 v24, v26, v27
	s_waitcnt lgkmcnt(12)
	v_cvt_pk_bf16_f32 v25, v28, v29
	s_waitcnt lgkmcnt(11)
	v_cvt_pk_bf16_f32 v26, v30, v31
	s_waitcnt lgkmcnt(10)
	v_cvt_pk_bf16_f32 v27, v32, v33
	s_waitcnt lgkmcnt(9)
	v_cvt_pk_bf16_f32 v28, v34, v35
	s_waitcnt lgkmcnt(8)
	v_cvt_pk_bf16_f32 v29, v36, v37
	s_waitcnt lgkmcnt(7)
	v_cvt_pk_bf16_f32 v30, v38, v39
	s_waitcnt lgkmcnt(6)
	v_cvt_pk_bf16_f32 v31, v40, v41
	s_waitcnt lgkmcnt(5)
	v_cvt_pk_bf16_f32 v32, v42, v43
	s_waitcnt lgkmcnt(4)
	v_cvt_pk_bf16_f32 v33, v44, v45
	s_waitcnt lgkmcnt(3)
	v_cvt_pk_bf16_f32 v34, v46, v47
	s_waitcnt lgkmcnt(2)
	v_cvt_pk_bf16_f32 v35, v48, v49
	s_waitcnt lgkmcnt(1)
	v_cvt_pk_bf16_f32 v36, v50, v51
	s_waitcnt lgkmcnt(0)
	v_cvt_pk_bf16_f32 v37, v52, v53
	global_store_dwordx4 v[54:55], v[22:25], off
	global_store_dwordx4 v[56:57], v[26:29], off
	global_store_dwordx4 v[58:59], v[30:33], off
	global_store_dwordx4 v[60:61], v[34:37], off
	s_barrier
	s_cbranch_scc1 .LBB0_33

; __device__ __forceinline__ float bf_lo(unsigned u) { return __uint_as_float(u << 16); }
; __device__ __forceinline__ float bf_hi(unsigned u) { return __uint_as_float(u & 0xffff0000u); }
; __device__ __forceinline__ int fresh_tid() { int t = threadIdx.x; asm volatile("" : "+v"(t)); return t; }
;     __device__ __forceinline__ void fused(f32x4 (&acc)[2][2][4][2], const Unit& u, int wr, int wc, int fr, int fq, float* smem) const {
;         const int tid = fresh_tid();
;         const float* mb = mod + (size_t)(u.pm >> 3) * NMOD;
;         const int cb = u.pn * BM + wc * 32 + 8 * fq, rl0 = wr * 64 + fr;
;         float* part = smem; float* rsv = smem + 1024;
;         f32x4 gt[2][2];
; #pragma unroll
;         for (int bj = 0; bj < 2; ++bj)
; #pragma unroll
;             for (int n = 0; n < 2; ++n) gt[bj][n] = *(const f32x4*)(mb + (MODE ? 5120 : 2048) + cb + bj * HALF + n * 4);
; #pragma unroll
;         for (int ai = 0; ai < 2; ++ai) {
;             f32x4 bs[4][2][2];
; #pragma unroll
;             for (int m = 0; m < 4; ++m) { const size_t ro = (size_t)(u.pm * BM + rl0 + ai * HALF + m * 16) * DM;
; #pragma unroll
;                 for (int bj = 0; bj < 2; ++bj)
; #pragma unroll
;                     for (int n = 0; n < 2; ++n) { const int c = cb + bj * HALF + n * 4;
;                         if (MODE) { const uint2 q = *(const uint2*)(X1 + ro + c); bs[m][bj][n] = (f32x4){bf_lo(q.x), bf_hi(q.x), bf_lo(q.y), bf_hi(q.y)}; }
;                         else bs[m][bj][n] = *(const f32x4*)(xp + ro + c); } }
;             __builtin_amdgcn_sched_barrier(0);
; #pragma unroll
;             for (int m = 0; m < 4; ++m) { float ss = 0.f;
; #pragma unroll
;                 for (int bj = 0; bj < 2; ++bj)
; #pragma unroll
;                     for (int n = 0; n < 2; ++n) { const f32x4 v = bs[m][bj][n] + gt[bj][n] * acc[ai][bj][m][n]; acc[ai][bj][m][n] = v; ss += v[0] * v[0] + v[1] * v[1] + v[2] * v[2] + v[3] * v[3]; }
;                 ss += __shfl_xor(ss, 16); ss += __shfl_xor(ss, 32);
;                 if (fq == 0) part[(rl0 + ai * HALF + m * 16) * 4 + wc] = ss; } }
.LBB0_535:
	s_ashr_i32 s0, s8, 3
	s_lshl_b32 s4, s33, 6
	s_mul_hi_i32 s1, s0, 0x6000
	s_mulk_i32 s0, 0x6000
	s_add_u32 s0, s16, s0
	s_addc_u32 s1, s17, s1
	s_lshl_b32 s5, s9, 8
	s_or_b32 s4, s5, s4
	v_lshl_or_b32 v194, v196, 3, s4
	v_ashrrev_i32_e32 v195, 31, v194
	v_lshlrev_b64 v[222:223], 2, v[194:195]
	v_lshl_add_u64 v[128:129], s[0:1], 0, v[222:223]
	s_mov_b64 s[4:5], 0x2000
	v_lshl_add_u64 v[132:133], v[128:129], 0, s[4:5]
	s_movk_i32 s4, 0x2000
	v_add_co_u32_e32 v128, vcc, s4, v128
	s_lshl_b32 s4, s8, 8
	v_add_u32_e32 v192, s4, v231
	v_ashrrev_i32_e32 v193, 31, v192
	v_lshlrev_b64 v[144:145], 12, v[192:193]
	v_lshl_add_u64 v[144:145], s[36:37], 0, v[144:145]
	v_mov_b32_e32 v202, v224
	v_addc_co_u32_e32 v129, vcc, 0, v129, vcc
	v_lshl_add_u64 v[144:145], v[144:145], 0, v[222:223]
	s_barrier
	global_load_dwordx4 v[140:143], v[128:129], off
	s_nop 0
	global_load_dwordx4 v[128:131], v[132:133], off offset:144
	global_load_dwordx4 v[136:139], v[132:133], off offset:16
	s_nop 0
	global_load_dwordx4 v[132:135], v[132:133], off offset:128
	s_nop 0
	global_load_dwordx4 v[198:201], v[144:145], off offset:16 nt
	global_load_dwordx4 v[204:207], v[144:145], off nt
	global_load_dwordx4 v[232:235], v[144:145], off offset:144 nt
	global_load_dwordx4 v[208:211], v[144:145], off offset:128 nt
	v_or_b32_e32 v144, 16, v192
	v_ashrrev_i32_e32 v145, 31, v144
	v_lshlrev_b64 v[144:145], 12, v[144:145]
	v_lshl_add_u64 v[144:145], s[36:37], 0, v[144:145]
	v_lshl_add_u64 v[144:145], v[144:145], 0, v[222:223]
	global_load_dwordx4 v[184:187], v[144:145], off offset:16 nt
	global_load_dwordx4 v[188:191], v[144:145], off nt
	global_load_dwordx4 v[176:179], v[144:145], off offset:144 nt
	global_load_dwordx4 v[180:183], v[144:145], off offset:128 nt
	v_or_b32_e32 v144, 32, v192
	v_ashrrev_i32_e32 v145, 31, v144
	v_lshlrev_b64 v[144:145], 12, v[144:145]
	v_lshl_add_u64 v[144:145], s[36:37], 0, v[144:145]
	v_lshl_add_u64 v[144:145], v[144:145], 0, v[222:223]
	global_load_dwordx4 v[168:171], v[144:145], off offset:16 nt
	global_load_dwordx4 v[172:175], v[144:145], off nt
	global_load_dwordx4 v[160:163], v[144:145], off offset:144 nt
	global_load_dwordx4 v[164:167], v[144:145], off offset:128 nt
	v_or_b32_e32 v144, 48, v192
	v_ashrrev_i32_e32 v145, 31, v144
	v_lshlrev_b64 v[144:145], 12, v[144:145]
	v_lshl_add_u64 v[144:145], s[36:37], 0, v[144:145]
	v_lshl_add_u64 v[148:149], v[144:145], 0, v[222:223]
	global_load_dwordx4 v[152:155], v[148:149], off offset:16 nt
	global_load_dwordx4 v[156:159], v[148:149], off nt
	global_load_dwordx4 v[144:147], v[148:149], off offset:144 nt
	s_nop 0
	global_load_dwordx4 v[148:151], v[148:149], off offset:128 nt
	s_lshl_b32 s4, s33, 2
	s_add_i32 s4, s4, 16
	v_cmp_eq_u32_e32 vcc, 0, v196
	v_lshl_add_u32 v203, v231, 4, s4
	s_waitcnt vmcnt(0)
	v_pk_fma_f32 v[216:217], v[124:125], v[140:141], v[204:205]
	v_pk_fma_f32 v[220:221], v[120:121], v[136:137], v[198:199]
	v_mul_f32_e32 v124, v217, v217
	v_mul_f32_e32 v120, v221, v221
	v_pk_fma_f32 v[208:209], v[116:117], v[132:133], v[208:209]
	v_pk_fma_f32 v[214:215], v[126:127], v[142:143], v[206:207]
	v_fmac_f32_e32 v124, v216, v216
	v_pk_fma_f32 v[218:219], v[122:123], v[138:139], v[200:201]
	v_fmac_f32_e32 v120, v220, v220
	v_mul_f32_e32 v116, v209, v209
	v_pk_fma_f32 v[212:213], v[108:109], v[128:129], v[232:233]
	v_fmac_f32_e32 v124, v214, v214
	v_fmac_f32_e32 v120, v218, v218
	v_pk_fma_f32 v[206:207], v[118:119], v[134:135], v[210:211]
	v_fmac_f32_e32 v116, v208, v208
	v_mul_f32_e32 v108, v213, v213
	v_fmac_f32_e32 v124, v215, v215
	v_fmac_f32_e32 v120, v219, v219
	v_fmac_f32_e32 v116, v206, v206
	v_pk_fma_f32 v[210:211], v[110:111], v[130:131], v[234:235]
	v_fmac_f32_e32 v108, v212, v212
	v_add_f32_e32 v120, v124, v120
	v_fmac_f32_e32 v116, v207, v207
	v_fmac_f32_e32 v108, v210, v210
	v_add_f32_e32 v116, v120, v116
	v_fmac_f32_e32 v108, v211, v211
	v_add_f32_e32 v108, v116, v108
	ds_bpermute_b32 v109, v229, v108
	s_waitcnt lgkmcnt(0)
	v_add_f32_e32 v108, v108, v109
	ds_bpermute_b32 v109, v230, v108
	s_and_saveexec_b64 s[4:5], vcc
	s_cbranch_execz .LBB0_537
	s_waitcnt lgkmcnt(0)
	v_add_f32_e32 v108, v108, v109
	ds_write_b32 v203, v108

; __device__ __forceinline__ float bf_lo(unsigned u) { return __uint_as_float(u << 16); }
; __device__ __forceinline__ float bf_hi(unsigned u) { return __uint_as_float(u & 0xffff0000u); }
;     __device__ __forceinline__ void fused(f32x4 (&acc)[2][2][4][2], const Unit& u, int wr, int wc, int fr, int fq, float* smem) const {
;     ...
;             for (int m = 0; m < 4; ++m) { const size_t ro = (size_t)(u.pm * BM + rl0 + ai * HALF + m * 16) * DM;
; #pragma unroll
;                 for (int bj = 0; bj < 2; ++bj)
; #pragma unroll
;                     for (int n = 0; n < 2; ++n) { const int c = cb + bj * HALF + n * 4;
;                         if (MODE) { const uint2 q = *(const uint2*)(X1 + ro + c); bs[m][bj][n] = (f32x4){bf_lo(q.x), bf_hi(q.x), bf_lo(q.y), bf_hi(q.y)}; }
;                         else bs[m][bj][n] = *(const f32x4*)(xp + ro + c); } }
;             __builtin_amdgcn_sched_barrier(0);
; #pragma unroll
;             for (int m = 0; m < 4; ++m) { float ss = 0.f;
; #pragma unroll
;                 for (int bj = 0; bj < 2; ++bj)
; #pragma unroll
;                     for (int n = 0; n < 2; ++n) { const f32x4 v = bs[m][bj][n] + gt[bj][n] * acc[ai][bj][m][n]; acc[ai][bj][m][n] = v; ss += v[0] * v[0] + v[1] * v[1] + v[2] * v[2] + v[3] * v[3]; }
;                 ss += __shfl_xor(ss, 16); ss += __shfl_xor(ss, 32);
;                 if (fq == 0) part[(rl0 + ai * HALF + m * 16) * 4 + wc] = ss; } }
.LBB0_543:
	s_or_b64 exec, exec, s[4:5]
	v_add_u32_e32 v124, 0x80, v192
	v_ashrrev_i32_e32 v125, 31, v124
	s_waitcnt lgkmcnt(0)
	v_lshlrev_b64 v[64:65], 12, v[124:125]
	v_lshl_add_u64 v[64:65], s[36:37], 0, v[64:65]
	v_add_u32_e32 v116, 0x90, v192
	v_lshl_add_u64 v[64:65], v[64:65], 0, v[222:223]
	v_ashrrev_i32_e32 v117, 31, v116
	global_load_dwordx4 v[144:147], v[64:65], off offset:16 nt
	global_load_dwordx4 v[148:151], v[64:65], off nt
	global_load_dwordx4 v[232:235], v[64:65], off offset:144 nt
	global_load_dwordx4 v[236:239], v[64:65], off offset:128 nt
	v_lshlrev_b64 v[64:65], 12, v[116:117]
	v_lshl_add_u64 v[64:65], s[36:37], 0, v[64:65]
	v_add_u32_e32 v114, 0xa0, v192
	v_lshl_add_u64 v[64:65], v[64:65], 0, v[222:223]
	v_ashrrev_i32_e32 v115, 31, v114
	global_load_dwordx4 v[104:107], v[64:65], off offset:16 nt
	global_load_dwordx4 v[108:111], v[64:65], off nt
	global_load_dwordx4 v[96:99], v[64:65], off offset:144 nt
	global_load_dwordx4 v[100:103], v[64:65], off offset:128 nt
	v_lshlrev_b64 v[64:65], 12, v[114:115]
	v_lshl_add_u64 v[64:65], s[36:37], 0, v[64:65]
	v_add_u32_e32 v112, 0xb0, v192
	v_lshl_add_u64 v[64:65], v[64:65], 0, v[222:223]
	v_ashrrev_i32_e32 v113, 31, v112
	global_load_dwordx4 v[88:91], v[64:65], off offset:16 nt
	global_load_dwordx4 v[92:95], v[64:65], off nt
	global_load_dwordx4 v[80:83], v[64:65], off offset:144 nt
	global_load_dwordx4 v[84:87], v[64:65], off offset:128 nt
	v_lshlrev_b64 v[64:65], 12, v[112:113]
	v_lshl_add_u64 v[64:65], s[36:37], 0, v[64:65]
	v_lshl_add_u64 v[68:69], v[64:65], 0, v[222:223]
	global_load_dwordx4 v[72:75], v[68:69], off offset:16 nt
	global_load_dwordx4 v[76:79], v[68:69], off nt
	global_load_dwordx4 v[64:67], v[68:69], off offset:144 nt
	s_nop 0
	global_load_dwordx4 v[68:71], v[68:69], off offset:128 nt
	s_waitcnt vmcnt(14)
	v_pk_fma_f32 v[168:169], v[60:61], v[140:141], v[148:149]
	v_pk_fma_f32 v[180:181], v[56:57], v[136:137], v[144:145]
	v_mul_f32_e32 v60, v169, v169
	v_pk_fma_f32 v[176:177], v[58:59], v[138:139], v[146:147]
	v_mul_f32_e32 v56, v181, v181
	s_waitcnt vmcnt(12)
	v_pk_fma_f32 v[146:147], v[52:53], v[132:133], v[236:237]
	v_pk_fma_f32 v[160:161], v[62:63], v[142:143], v[150:151]
	v_fmac_f32_e32 v60, v168, v168
	v_fmac_f32_e32 v56, v180, v180
	v_mul_f32_e32 v52, v147, v147
	v_pk_fma_f32 v[150:151], v[44:45], v[128:129], v[232:233]
	v_fmac_f32_e32 v60, v160, v160
	v_fmac_f32_e32 v56, v176, v176
	v_pk_fma_f32 v[144:145], v[54:55], v[134:135], v[238:239]
	v_fmac_f32_e32 v52, v146, v146
	v_mul_f32_e32 v44, v151, v151
	v_fmac_f32_e32 v60, v161, v161
	v_fmac_f32_e32 v56, v177, v177
	v_fmac_f32_e32 v52, v144, v144
	v_pk_fma_f32 v[148:149], v[46:47], v[130:131], v[234:235]
	v_fmac_f32_e32 v44, v150, v150
	v_add_f32_e32 v56, v60, v56
	v_fmac_f32_e32 v52, v145, v145
	v_fmac_f32_e32 v44, v148, v148
	v_add_f32_e32 v52, v56, v52
	v_fmac_f32_e32 v44, v149, v149
	v_add_f32_e32 v44, v52, v44
	ds_bpermute_b32 v45, v229, v44
	s_waitcnt lgkmcnt(0)
	v_add_f32_e32 v44, v44, v45
	ds_bpermute_b32 v45, v230, v44
	s_and_saveexec_b64 s[4:5], vcc
	s_cbranch_execz .LBB0_545
	s_waitcnt lgkmcnt(0)
	v_add_f32_e32 v44, v44, v45
	ds_write_b32 v203, v44 offset:2048

; __device__ __forceinline__ void st_bf16x8(bf16_t* p, const f32x4 a, const f32x4 b) { uint4 o; o.x = cvt_pk_bf16(a[0], a[1]); o.y = cvt_pk_bf16(a[2], a[3]); o.z = cvt_pk_bf16(b[0], b[1]); o.w = cvt_pk_bf16(b[2], b[3]); *(uint4*)p = o; }
;     __device__ __forceinline__ void fused(f32x4 (&acc)[2][2][4][2], const Unit& u, int wr, int wc, int fr, int fq, float* smem) const {
;     ...
;         f32x4 gs[2][2], sh[2][2];
; #pragma unroll
;         for (int bj = 0; bj < 2; ++bj)
; #pragma unroll
;             for (int n = 0; n < 2; ++n) { const int c = cb + bj * HALF + n * 4; gs[bj][n] = *(const f32x4*)(g + c);
;                 if (MODE == 0) { gs[bj][n] = gs[bj][n] * (*(const f32x4*)(mb + 4096 + c) + 1.f); sh[bj][n] = *(const f32x4*)(mb + 3072 + c); } }
;         __syncthreads();
;         if (tid < 256) { float s = 0.f;
; #pragma unroll
;             for (int q = 0; q < 4; ++q) s += __hip_atomic_load(slots + (size_t)(u.pm * 4 + q) * 256 + tid, __ATOMIC_RELAXED, __HIP_MEMORY_SCOPE_AGENT);
;             rsv[tid] = rsqrtf(s * (1.f / DM) + EPS); }
;         __syncthreads();
; #pragma unroll
;         for (int ai = 0; ai < 2; ++ai)
; #pragma unroll
;             for (int m = 0; m < 4; ++m) { const int rl = rl0 + ai * HALF + m * 16; const size_t ro = (size_t)(u.pm * BM + rl) * DM; const float r = rsv[rl];
; #pragma unroll
;                 for (int bj = 0; bj < 2; ++bj) { const int c = cb + bj * HALF; const f32x4 v0 = acc[ai][bj][m][0], v1 = acc[ai][bj][m][1];
;                     if (MODE == 0) { st_bf16x8(X1 + ro + c, v0, v1); st_bf16x8(H + ro + c, v0 * r * gs[bj][0] + sh[bj][0], v1 * r * gs[bj][1] + sh[bj][1]); }
;                     else { *(f32x4*)(out + ro + c) = v0 * r * gs[bj][0]; *(f32x4*)(out + ro + c + 4) = v1 * r * gs[bj][1]; } } }
.LBB0_569:
	s_or_b64 exec, exec, s[20:21]
	s_add_u32 s12, s0, 0x4000
	s_addc_u32 s13, s1, 0
	s_add_u32 s0, s0, 0x3000
	v_or_b32_e32 v0, 32, v194
	s_addc_u32 s1, s1, 0
	v_lshl_add_u64 v[4:5], s[28:29], 0, v[222:223]
	v_lshl_add_u64 v[6:7], s[12:13], 0, v[222:223]
	v_ashrrev_i32_e32 v1, 31, v0
	v_or_b32_e32 v2, 36, v194
	global_load_dwordx4 v[20:23], v[4:5], off offset:16
	global_load_dwordx4 v[16:19], v[4:5], off
	global_load_dwordx4 v[28:31], v[6:7], off offset:16
	global_load_dwordx4 v[24:27], v[6:7], off
	v_lshl_add_u64 v[6:7], s[0:1], 0, v[222:223]
	v_ashrrev_i32_e32 v3, 31, v2
	global_load_dwordx4 v[8:11], v[6:7], off offset:16
	global_load_dwordx4 v[12:15], v[6:7], off
	global_load_dwordx4 v[36:39], v[4:5], off offset:144
	global_load_dwordx4 v[32:35], v[4:5], off offset:128
	v_lshlrev_b64 v[0:1], 2, v[0:1]
	v_lshl_add_u64 v[4:5], s[12:13], 0, v[0:1]
	v_lshl_add_u64 v[0:1], s[0:1], 0, v[0:1]
	v_lshl_add_u64 v[44:45], v[2:3], 2, s[12:13]
	global_load_dwordx4 v[40:43], v[4:5], off
	s_nop 0
	global_load_dwordx4 v[4:7], v[0:1], off
	s_nop 0
	global_load_dwordx4 v[0:3], v[0:1], off offset:16
	s_nop 0
	global_load_dwordx4 v[44:47], v[44:45], off
	s_barrier
	s_and_saveexec_b64 s[0:1], s[4:5]
	s_cbranch_execz .LBB0_571
	s_lshl_b32 s4, s8, 2
	s_ashr_i32 s5, s4, 31
	v_lshl_add_u64 v[64:65], v[202:203], 2, s[6:7]
	s_lshl_b64 s[6:7], s[4:5], 10
	v_lshl_add_u64 v[66:67], v[64:65], 0, s[6:7]
	s_or_b32 s6, s4, 1
	s_ashr_i32 s7, s6, 31
	s_lshl_b64 s[6:7], s[6:7], 10
	global_load_dword v68, v[66:67], off sc1
	v_lshl_add_u64 v[66:67], v[64:65], 0, s[6:7]
	s_or_b32 s6, s4, 2
	s_ashr_i32 s7, s6, 31
	s_or_b32 s4, s4, 3
	s_lshl_b64 s[6:7], s[6:7], 10
	s_ashr_i32 s5, s4, 31
	global_load_dword v69, v[66:67], off sc1
	v_lshl_add_u64 v[66:67], v[64:65], 0, s[6:7]
	s_lshl_b64 s[4:5], s[4:5], 10
	global_load_dword v66, v[66:67], off sc1
	v_lshl_add_u64 v[64:65], v[64:65], 0, s[4:5]
	global_load_dword v64, v[64:65], off sc1
	v_mov_b32_e32 v65, 0x358637bd
	s_mov_b32 s4, 0x800000
	s_waitcnt vmcnt(3)
	v_add_f32_e32 v67, 0, v68
	s_waitcnt vmcnt(2)
	v_add_f32_e32 v67, v67, v69
	s_waitcnt vmcnt(1)
	v_add_f32_e32 v66, v67, v66
	s_waitcnt vmcnt(0)
	v_add_f32_e32 v64, v66, v64
	v_fmac_f32_e32 v65, 0x3a800000, v64
	v_mul_f32_e32 v64, 0x4b800000, v65
	v_cmp_gt_f32_e32 vcc, s4, v65
	s_nop 1
	v_cndmask_b32_e32 v64, v65, v64, vcc
	v_rsq_f32_e32 v64, v64
	s_nop 0
	v_mul_f32_e32 v65, 0x45800000, v64
	v_cndmask_b32_e32 v64, v64, v65, vcc
	v_lshl_add_u32 v65, v202, 2, 16
	ds_write_b32 v65, v64 offset:4096
.LBB0_571:
	s_or_b64 exec, exec, s[0:1]
	s_waitcnt vmcnt(0)
	v_pk_add_f32 v[24:25], v[24:25], 1.0 op_sel_hi:[1,0]
	v_pk_mul_f32 v[16:17], v[16:17], v[24:25]
	v_pk_add_f32 v[26:27], v[26:27], 1.0 op_sel_hi:[1,0]
	v_pk_mul_f32 v[18:19], v[18:19], v[26:27]
	v_pk_add_f32 v[28:29], v[28:29], 1.0 op_sel_hi:[1,0]
	v_pk_mul_f32 v[20:21], v[20:21], v[28:29]
	v_pk_add_f32 v[30:31], v[30:31], 1.0 op_sel_hi:[1,0]
	v_pk_mul_f32 v[22:23], v[22:23], v[30:31]
	v_pk_add_f32 v[40:41], v[40:41], 1.0 op_sel_hi:[1,0]
	v_pk_mul_f32 v[32:33], v[32:33], v[40:41]
	v_pk_add_f32 v[42:43], v[42:43], 1.0 op_sel_hi:[1,0]
	v_pk_mul_f32 v[34:35], v[34:35], v[42:43]
	v_pk_add_f32 v[44:45], v[44:45], 1.0 op_sel_hi:[1,0]
	v_pk_mul_f32 v[36:37], v[36:37], v[44:45]
	v_pk_add_f32 v[46:47], v[46:47], 1.0 op_sel_hi:[1,0]
	v_pk_mul_f32 v[38:39], v[38:39], v[46:47]
	v_lshl_add_u32 v124, v231, 2, 16
	v_add_u32_e32 v124, 0x1000, v124
	s_waitcnt lgkmcnt(0)
	s_barrier
	ds_read2_b32 v[64:65], v124 offset1:16
	ds_read2_b32 v[66:67], v124 offset0:32 offset1:48
	ds_read2_b32 v[68:69], v124 offset0:128 offset1:144
	ds_read2_b32 v[70:71], v124 offset0:160 offset1:176
	v_and_b32_e32 v202, 1, v192
	v_and_b32_e32 v222, -2, v192
	v_mov_b32_e32 v223, v193
	v_lshlrev_b64 v[222:223], 11, v[222:223]
	v_lshlrev_b64 v[124:125], 1, v[194:195]
	v_lshl_add_u64 v[222:223], v[222:223], 0, v[124:125]
	v_lshlrev_b32_e32 v124, 6, v202
	v_mov_b32_e32 v125, 0
	v_lshl_add_u64 v[222:223], v[222:223], 0, v[124:125]
	v_lshl_add_u64 v[86:87], s[18:19], 0, v[222:223]
	v_lshl_add_u64 v[116:117], s[26:27], 0, v[222:223]
	s_mov_b32 s64, 0x55555555
	s_mov_b32 s65, 0x55555555
	s_mov_b32 s66, 0xaaaaaaaa
	s_mov_b32 s67, 0xaaaaaaaa
	s_mov_b64 s[68:69], 0x8000
	s_mov_b64 s[70:71], 0x28000
	v_mov_b32_e32 v75, 0
	s_waitcnt lgkmcnt(0)
; __device__ __forceinline__ unsigned cvt_pk_bf16(float lo, float hi) { unsigned r; asm("v_cvt_pk_bf16_f32 %0, %1, %2" : "=v"(r) : "v"(lo), "v"(hi)); return r; }
; __device__ __forceinline__ void st_bf16x8(bf16_t* p, const f32x4 a, const f32x4 b) { uint4 o; o.x = cvt_pk_bf16(a[0], a[1]); o.y = cvt_pk_bf16(a[2], a[3]); o.z = cvt_pk_bf16(b[0], b[1]); o.w = cvt_pk_bf16(b[2], b[3]); *(uint4*)p = o; }
;     __device__ __forceinline__ void fused(f32x4 (&acc)[2][2][4][2], const Unit& u, int wr, int wc, int fr, int fq, float* smem) const {
;     ...
; #pragma unroll
;         for (int ai = 0; ai < 2; ++ai)
; #pragma unroll
;             for (int m = 0; m < 4; ++m) { const int rl = rl0 + ai * HALF + m * 16; const size_t ro = (size_t)(u.pm * BM + rl) * DM; const float r = rsv[rl];
; #pragma unroll
;                 for (int bj = 0; bj < 2; ++bj) { const int c = cb + bj * HALF; const f32x4 v0 = acc[ai][bj][m][0], v1 = acc[ai][bj][m][1];
;                     if (MODE == 0) { st_bf16x8(X1 + ro + c, v0, v1); st_bf16x8(H + ro + c, v0 * r * gs[bj][0] + sh[bj][0], v1 * r * gs[bj][1] + sh[bj][1]); }
;                     else { *(f32x4*)(out + ro + c) = v0 * r * gs[bj][0]; *(f32x4*)(out + ro + c + 4) = v1 * r * gs[bj][1]; } } }
	v_mov_b32_e32 v74, v64
	v_cvt_pk_bf16_f32 v128, v216, v217
	v_cvt_pk_bf16_f32 v129, v214, v215
	v_cvt_pk_bf16_f32 v130, v220, v221
	v_cvt_pk_bf16_f32 v131, v218, v219
	v_cvt_pk_bf16_f32 v132, v208, v209
	v_cvt_pk_bf16_f32 v133, v206, v207
	v_cvt_pk_bf16_f32 v134, v212, v213
	v_cvt_pk_bf16_f32 v135, v210, v211
	v_pk_mul_f32 v[232:233], v[216:217], v[74:75] op_sel_hi:[1,0]
	v_pk_mul_f32 v[234:235], v[214:215], v[74:75] op_sel_hi:[1,0]
	v_pk_mul_f32 v[236:237], v[220:221], v[74:75] op_sel_hi:[1,0]
	v_pk_mul_f32 v[238:239], v[218:219], v[74:75] op_sel_hi:[1,0]
	v_pk_fma_f32 v[232:233], v[16:17], v[232:233], v[12:13]
	v_pk_fma_f32 v[234:235], v[18:19], v[234:235], v[14:15]
	v_pk_fma_f32 v[236:237], v[20:21], v[236:237], v[8:9]
	v_pk_fma_f32 v[238:239], v[22:23], v[238:239], v[10:11]
	v_cvt_pk_bf16_f32 v112, v232, v233
	v_cvt_pk_bf16_f32 v113, v234, v235
	v_cvt_pk_bf16_f32 v114, v236, v237
	v_cvt_pk_bf16_f32 v115, v238, v239
	v_pk_mul_f32 v[232:233], v[208:209], v[74:75] op_sel_hi:[1,0]
	v_pk_mul_f32 v[234:235], v[206:207], v[74:75] op_sel_hi:[1,0]
	v_pk_mul_f32 v[236:237], v[212:213], v[74:75] op_sel_hi:[1,0]
	v_pk_mul_f32 v[238:239], v[210:211], v[74:75] op_sel_hi:[1,0]
	v_pk_fma_f32 v[232:233], v[32:33], v[232:233], v[4:5]
	v_pk_fma_f32 v[234:235], v[34:35], v[234:235], v[6:7]
	v_pk_fma_f32 v[236:237], v[36:37], v[236:237], v[0:1]
	v_pk_fma_f32 v[238:239], v[38:39], v[238:239], v[2:3]
	v_cvt_pk_bf16_f32 v76, v232, v233
	v_cvt_pk_bf16_f32 v77, v234, v235
	v_cvt_pk_bf16_f32 v78, v236, v237
	v_cvt_pk_bf16_f32 v79, v238, v239
	s_mov_b64 vcc, s[64:65]
	s_nop 0
	v_cndmask_b32_dpp v136, v132, v128, vcc quad_perm:[1,0,3,2] row_mask:0xf bank_mask:0xf
	v_cndmask_b32_dpp v137, v133, v129, vcc quad_perm:[1,0,3,2] row_mask:0xf bank_mask:0xf
	v_cndmask_b32_dpp v138, v134, v130, vcc quad_perm:[1,0,3,2] row_mask:0xf bank_mask:0xf
	v_cndmask_b32_dpp v139, v135, v131, vcc quad_perm:[1,0,3,2] row_mask:0xf bank_mask:0xf
	s_mov_b64 vcc, s[66:67]
	v_cndmask_b32_dpp v140, v128, v132, vcc quad_perm:[1,0,3,2] row_mask:0xf bank_mask:0xf
	v_cndmask_b32_dpp v141, v129, v133, vcc quad_perm:[1,0,3,2] row_mask:0xf bank_mask:0xf
	v_cndmask_b32_dpp v142, v130, v134, vcc quad_perm:[1,0,3,2] row_mask:0xf bank_mask:0xf
	v_cndmask_b32_dpp v143, v131, v135, vcc quad_perm:[1,0,3,2] row_mask:0xf bank_mask:0xf
	global_store_dwordx4 v[86:87], v[136:139], off
	global_store_dwordx4 v[86:87], v[140:143], off offset:2048
	s_mov_b64 vcc, s[64:65]
	s_nop 0
	v_cndmask_b32_dpp v136, v76, v112, vcc quad_perm:[1,0,3,2] row_mask:0xf bank_mask:0xf
	v_cndmask_b32_dpp v137, v77, v113, vcc quad_perm:[1,0,3,2] row_mask:0xf bank_mask:0xf
	v_cndmask_b32_dpp v138, v78, v114, vcc quad_perm:[1,0,3,2] row_mask:0xf bank_mask:0xf
	v_cndmask_b32_dpp v139, v79, v115, vcc quad_perm:[1,0,3,2] row_mask:0xf bank_mask:0xf
	s_mov_b64 vcc, s[66:67]
	v_cndmask_b32_dpp v140, v112, v76, vcc quad_perm:[1,0,3,2] row_mask:0xf bank_mask:0xf
	v_cndmask_b32_dpp v141, v113, v77, vcc quad_perm:[1,0,3,2] row_mask:0xf bank_mask:0xf
	v_cndmask_b32_dpp v142, v114, v78, vcc quad_perm:[1,0,3,2] row_mask:0xf bank_mask:0xf
	v_cndmask_b32_dpp v143, v115, v79, vcc quad_perm:[1,0,3,2] row_mask:0xf bank_mask:0xf
	global_store_dwordx4 v[116:117], v[136:139], off
	global_store_dwordx4 v[116:117], v[140:143], off offset:2048
	v_lshl_add_u64 v[86:87], v[86:87], 0, s[68:69]
	v_lshl_add_u64 v[116:117], v[116:117], 0, s[68:69]
	v_mov_b32_e32 v74, v65
	v_cvt_pk_bf16_f32 v128, v198, v199
	v_cvt_pk_bf16_f32 v129, v196, v197
	v_cvt_pk_bf16_f32 v130, v204, v205
	v_cvt_pk_bf16_f32 v131, v200, v201
	v_cvt_pk_bf16_f32 v132, v184, v185
	v_cvt_pk_bf16_f32 v133, v182, v183
	v_cvt_pk_bf16_f32 v134, v190, v191
	v_cvt_pk_bf16_f32 v135, v188, v189
	v_pk_mul_f32 v[232:233], v[198:199], v[74:75] op_sel_hi:[1,0]
	v_pk_mul_f32 v[234:235], v[196:197], v[74:75] op_sel_hi:[1,0]
	v_pk_mul_f32 v[236:237], v[204:205], v[74:75] op_sel_hi:[1,0]
	v_pk_mul_f32 v[238:239], v[200:201], v[74:75] op_sel_hi:[1,0]
	v_pk_fma_f32 v[232:233], v[16:17], v[232:233], v[12:13]
	v_pk_fma_f32 v[234:235], v[18:19], v[234:235], v[14:15]
	v_pk_fma_f32 v[236:237], v[20:21], v[236:237], v[8:9]
	v_pk_fma_f32 v[238:239], v[22:23], v[238:239], v[10:11]
	v_cvt_pk_bf16_f32 v112, v232, v233
	v_cvt_pk_bf16_f32 v113, v234, v235
	v_cvt_pk_bf16_f32 v114, v236, v237
	v_cvt_pk_bf16_f32 v115, v238, v239
	v_pk_mul_f32 v[232:233], v[184:185], v[74:75] op_sel_hi:[1,0]
	v_pk_mul_f32 v[234:235], v[182:183], v[74:75] op_sel_hi:[1,0]
	v_pk_mul_f32 v[236:237], v[190:191], v[74:75] op_sel_hi:[1,0]
	v_pk_mul_f32 v[238:239], v[188:189], v[74:75] op_sel_hi:[1,0]
	v_pk_fma_f32 v[232:233], v[32:33], v[232:233], v[4:5]
	v_pk_fma_f32 v[234:235], v[34:35], v[234:235], v[6:7]
	v_pk_fma_f32 v[236:237], v[36:37], v[236:237], v[0:1]
	v_pk_fma_f32 v[238:239], v[38:39], v[238:239], v[2:3]
	v_cvt_pk_bf16_f32 v76, v232, v233
	v_cvt_pk_bf16_f32 v77, v234, v235
	v_cvt_pk_bf16_f32 v78, v236, v237
	v_cvt_pk_bf16_f32 v79, v238, v239
	s_mov_b64 vcc, s[64:65]
	s_nop 0
	v_cndmask_b32_dpp v136, v132, v128, vcc quad_perm:[1,0,3,2] row_mask:0xf bank_mask:0xf
	v_cndmask_b32_dpp v137, v133, v129, vcc quad_perm:[1,0,3,2] row_mask:0xf bank_mask:0xf
	v_cndmask_b32_dpp v138, v134, v130, vcc quad_perm:[1,0,3,2] row_mask:0xf bank_mask:0xf
	v_cndmask_b32_dpp v139, v135, v131, vcc quad_perm:[1,0,3,2] row_mask:0xf bank_mask:0xf
	s_mov_b64 vcc, s[66:67]
	v_cndmask_b32_dpp v140, v128, v132, vcc quad_perm:[1,0,3,2] row_mask:0xf bank_mask:0xf
	v_cndmask_b32_dpp v141, v129, v133, vcc quad_perm:[1,0,3,2] row_mask:0xf bank_mask:0xf
	v_cndmask_b32_dpp v142, v130, v134, vcc quad_perm:[1,0,3,2] row_mask:0xf bank_mask:0xf
; __device__ __forceinline__ unsigned cvt_pk_bf16(float lo, float hi) { unsigned r; asm("v_cvt_pk_bf16_f32 %0, %1, %2" : "=v"(r) : "v"(lo), "v"(hi)); return r; }
; __device__ __forceinline__ void st_bf16x8(bf16_t* p, const f32x4 a, const f32x4 b) { uint4 o; o.x = cvt_pk_bf16(a[0], a[1]); o.y = cvt_pk_bf16(a[2], a[3]); o.z = cvt_pk_bf16(b[0], b[1]); o.w = cvt_pk_bf16(b[2], b[3]); *(uint4*)p = o; }
;     __device__ __forceinline__ void fused(f32x4 (&acc)[2][2][4][2], const Unit& u, int wr, int wc, int fr, int fq, float* smem) const {
;     ...
; #pragma unroll
;         for (int ai = 0; ai < 2; ++ai)
; #pragma unroll
;             for (int m = 0; m < 4; ++m) { const int rl = rl0 + ai * HALF + m * 16; const size_t ro = (size_t)(u.pm * BM + rl) * DM; const float r = rsv[rl];
; #pragma unroll
;                 for (int bj = 0; bj < 2; ++bj) { const int c = cb + bj * HALF; const f32x4 v0 = acc[ai][bj][m][0], v1 = acc[ai][bj][m][1];
;                     if (MODE == 0) { st_bf16x8(X1 + ro + c, v0, v1); st_bf16x8(H + ro + c, v0 * r * gs[bj][0] + sh[bj][0], v1 * r * gs[bj][1] + sh[bj][1]); }
;                     else { *(f32x4*)(out + ro + c) = v0 * r * gs[bj][0]; *(f32x4*)(out + ro + c + 4) = v1 * r * gs[bj][1]; } } }
	v_cndmask_b32_dpp v143, v131, v135, vcc quad_perm:[1,0,3,2] row_mask:0xf bank_mask:0xf
	global_store_dwordx4 v[86:87], v[136:139], off
	global_store_dwordx4 v[86:87], v[140:143], off offset:2048
	s_mov_b64 vcc, s[64:65]
	s_nop 0
	v_cndmask_b32_dpp v136, v76, v112, vcc quad_perm:[1,0,3,2] row_mask:0xf bank_mask:0xf
	v_cndmask_b32_dpp v137, v77, v113, vcc quad_perm:[1,0,3,2] row_mask:0xf bank_mask:0xf
	v_cndmask_b32_dpp v138, v78, v114, vcc quad_perm:[1,0,3,2] row_mask:0xf bank_mask:0xf
	v_cndmask_b32_dpp v139, v79, v115, vcc quad_perm:[1,0,3,2] row_mask:0xf bank_mask:0xf
	s_mov_b64 vcc, s[66:67]
	v_cndmask_b32_dpp v140, v112, v76, vcc quad_perm:[1,0,3,2] row_mask:0xf bank_mask:0xf
	v_cndmask_b32_dpp v141, v113, v77, vcc quad_perm:[1,0,3,2] row_mask:0xf bank_mask:0xf
	v_cndmask_b32_dpp v142, v114, v78, vcc quad_perm:[1,0,3,2] row_mask:0xf bank_mask:0xf
	v_cndmask_b32_dpp v143, v115, v79, vcc quad_perm:[1,0,3,2] row_mask:0xf bank_mask:0xf
	global_store_dwordx4 v[116:117], v[136:139], off
	global_store_dwordx4 v[116:117], v[140:143], off offset:2048
	v_lshl_add_u64 v[86:87], v[86:87], 0, s[68:69]
	v_lshl_add_u64 v[116:117], v[116:117], 0, s[68:69]
	v_mov_b32_e32 v74, v66
	v_cvt_pk_bf16_f32 v128, v172, v173
	v_cvt_pk_bf16_f32 v129, v174, v175
	v_cvt_pk_bf16_f32 v130, v186, v187
	v_cvt_pk_bf16_f32 v131, v178, v179
	v_cvt_pk_bf16_f32 v132, v164, v165
	v_cvt_pk_bf16_f32 v133, v166, v167
	v_cvt_pk_bf16_f32 v134, v170, v171
	v_cvt_pk_bf16_f32 v135, v162, v163
	v_pk_mul_f32 v[232:233], v[172:173], v[74:75] op_sel_hi:[1,0]
	v_pk_mul_f32 v[234:235], v[174:175], v[74:75] op_sel_hi:[1,0]
	v_pk_mul_f32 v[236:237], v[186:187], v[74:75] op_sel_hi:[1,0]
	v_pk_mul_f32 v[238:239], v[178:179], v[74:75] op_sel_hi:[1,0]
	v_pk_fma_f32 v[232:233], v[16:17], v[232:233], v[12:13]
	v_pk_fma_f32 v[234:235], v[18:19], v[234:235], v[14:15]
	v_pk_fma_f32 v[236:237], v[20:21], v[236:237], v[8:9]
	v_pk_fma_f32 v[238:239], v[22:23], v[238:239], v[10:11]
	v_cvt_pk_bf16_f32 v112, v232, v233
	v_cvt_pk_bf16_f32 v113, v234, v235
	v_cvt_pk_bf16_f32 v114, v236, v237
	v_cvt_pk_bf16_f32 v115, v238, v239
	v_pk_mul_f32 v[232:233], v[164:165], v[74:75] op_sel_hi:[1,0]
	v_pk_mul_f32 v[234:235], v[166:167], v[74:75] op_sel_hi:[1,0]
	v_pk_mul_f32 v[236:237], v[170:171], v[74:75] op_sel_hi:[1,0]
	v_pk_mul_f32 v[238:239], v[162:163], v[74:75] op_sel_hi:[1,0]
	v_pk_fma_f32 v[232:233], v[32:33], v[232:233], v[4:5]
	v_pk_fma_f32 v[234:235], v[34:35], v[234:235], v[6:7]
	v_pk_fma_f32 v[236:237], v[36:37], v[236:237], v[0:1]
	v_pk_fma_f32 v[238:239], v[38:39], v[238:239], v[2:3]
	v_cvt_pk_bf16_f32 v76, v232, v233
	v_cvt_pk_bf16_f32 v77, v234, v235
	v_cvt_pk_bf16_f32 v78, v236, v237
	v_cvt_pk_bf16_f32 v79, v238, v239
	s_mov_b64 vcc, s[64:65]
	s_nop 0
	v_cndmask_b32_dpp v136, v132, v128, vcc quad_perm:[1,0,3,2] row_mask:0xf bank_mask:0xf
	v_cndmask_b32_dpp v137, v133, v129, vcc quad_perm:[1,0,3,2] row_mask:0xf bank_mask:0xf
	v_cndmask_b32_dpp v138, v134, v130, vcc quad_perm:[1,0,3,2] row_mask:0xf bank_mask:0xf
	v_cndmask_b32_dpp v139, v135, v131, vcc quad_perm:[1,0,3,2] row_mask:0xf bank_mask:0xf
	s_mov_b64 vcc, s[66:67]
	v_cndmask_b32_dpp v140, v128, v132, vcc quad_perm:[1,0,3,2] row_mask:0xf bank_mask:0xf
	v_cndmask_b32_dpp v141, v129, v133, vcc quad_perm:[1,0,3,2] row_mask:0xf bank_mask:0xf
	v_cndmask_b32_dpp v142, v130, v134, vcc quad_perm:[1,0,3,2] row_mask:0xf bank_mask:0xf
	v_cndmask_b32_dpp v143, v131, v135, vcc quad_perm:[1,0,3,2] row_mask:0xf bank_mask:0xf
	global_store_dwordx4 v[86:87], v[136:139], off
	global_store_dwordx4 v[86:87], v[140:143], off offset:2048
	s_mov_b64 vcc, s[64:65]
	s_nop 0
	v_cndmask_b32_dpp v136, v76, v112, vcc quad_perm:[1,0,3,2] row_mask:0xf bank_mask:0xf
	v_cndmask_b32_dpp v137, v77, v113, vcc quad_perm:[1,0,3,2] row_mask:0xf bank_mask:0xf
	v_cndmask_b32_dpp v138, v78, v114, vcc quad_perm:[1,0,3,2] row_mask:0xf bank_mask:0xf
	v_cndmask_b32_dpp v139, v79, v115, vcc quad_perm:[1,0,3,2] row_mask:0xf bank_mask:0xf
	s_mov_b64 vcc, s[66:67]
	v_cndmask_b32_dpp v140, v112, v76, vcc quad_perm:[1,0,3,2] row_mask:0xf bank_mask:0xf
	v_cndmask_b32_dpp v141, v113, v77, vcc quad_perm:[1,0,3,2] row_mask:0xf bank_mask:0xf
	v_cndmask_b32_dpp v142, v114, v78, vcc quad_perm:[1,0,3,2] row_mask:0xf bank_mask:0xf
	v_cndmask_b32_dpp v143, v115, v79, vcc quad_perm:[1,0,3,2] row_mask:0xf bank_mask:0xf
	global_store_dwordx4 v[116:117], v[136:139], off
	global_store_dwordx4 v[116:117], v[140:143], off offset:2048
	v_lshl_add_u64 v[86:87], v[86:87], 0, s[68:69]
	v_lshl_add_u64 v[116:117], v[116:117], 0, s[68:69]
	v_mov_b32_e32 v74, v67
	v_cvt_pk_bf16_f32 v128, v156, v157
	v_cvt_pk_bf16_f32 v129, v158, v159
	v_cvt_pk_bf16_f32 v130, v152, v153
	v_cvt_pk_bf16_f32 v131, v154, v155
	v_cvt_pk_bf16_f32 v132, v120, v121
	v_cvt_pk_bf16_f32 v133, v118, v119
	v_cvt_pk_bf16_f32 v134, v126, v127
	v_cvt_pk_bf16_f32 v135, v122, v123
	v_pk_mul_f32 v[232:233], v[156:157], v[74:75] op_sel_hi:[1,0]
	v_pk_mul_f32 v[234:235], v[158:159], v[74:75] op_sel_hi:[1,0]
	v_pk_mul_f32 v[236:237], v[152:153], v[74:75] op_sel_hi:[1,0]
	v_pk_mul_f32 v[238:239], v[154:155], v[74:75] op_sel_hi:[1,0]
	v_pk_fma_f32 v[232:233], v[16:17], v[232:233], v[12:13]
	v_pk_fma_f32 v[234:235], v[18:19], v[234:235], v[14:15]
	v_pk_fma_f32 v[236:237], v[20:21], v[236:237], v[8:9]
	v_pk_fma_f32 v[238:239], v[22:23], v[238:239], v[10:11]
	v_cvt_pk_bf16_f32 v112, v232, v233
	v_cvt_pk_bf16_f32 v113, v234, v235
	v_cvt_pk_bf16_f32 v114, v236, v237
	v_cvt_pk_bf16_f32 v115, v238, v239
	v_pk_mul_f32 v[232:233], v[120:121], v[74:75] op_sel_hi:[1,0]
	v_pk_mul_f32 v[234:235], v[118:119], v[74:75] op_sel_hi:[1,0]
	v_pk_mul_f32 v[236:237], v[126:127], v[74:75] op_sel_hi:[1,0]
; __device__ __forceinline__ unsigned cvt_pk_bf16(float lo, float hi) { unsigned r; asm("v_cvt_pk_bf16_f32 %0, %1, %2" : "=v"(r) : "v"(lo), "v"(hi)); return r; }
; __device__ __forceinline__ void st_bf16x8(bf16_t* p, const f32x4 a, const f32x4 b) { uint4 o; o.x = cvt_pk_bf16(a[0], a[1]); o.y = cvt_pk_bf16(a[2], a[3]); o.z = cvt_pk_bf16(b[0], b[1]); o.w = cvt_pk_bf16(b[2], b[3]); *(uint4*)p = o; }
;     __device__ __forceinline__ void fused(f32x4 (&acc)[2][2][4][2], const Unit& u, int wr, int wc, int fr, int fq, float* smem) const {
;     ...
; #pragma unroll
;         for (int ai = 0; ai < 2; ++ai)
; #pragma unroll
;             for (int m = 0; m < 4; ++m) { const int rl = rl0 + ai * HALF + m * 16; const size_t ro = (size_t)(u.pm * BM + rl) * DM; const float r = rsv[rl];
; #pragma unroll
;                 for (int bj = 0; bj < 2; ++bj) { const int c = cb + bj * HALF; const f32x4 v0 = acc[ai][bj][m][0], v1 = acc[ai][bj][m][1];
;                     if (MODE == 0) { st_bf16x8(X1 + ro + c, v0, v1); st_bf16x8(H + ro + c, v0 * r * gs[bj][0] + sh[bj][0], v1 * r * gs[bj][1] + sh[bj][1]); }
;                     else { *(f32x4*)(out + ro + c) = v0 * r * gs[bj][0]; *(f32x4*)(out + ro + c + 4) = v1 * r * gs[bj][1]; } } }
	v_pk_mul_f32 v[238:239], v[122:123], v[74:75] op_sel_hi:[1,0]
	v_pk_fma_f32 v[232:233], v[32:33], v[232:233], v[4:5]
	v_pk_fma_f32 v[234:235], v[34:35], v[234:235], v[6:7]
	v_pk_fma_f32 v[236:237], v[36:37], v[236:237], v[0:1]
	v_pk_fma_f32 v[238:239], v[38:39], v[238:239], v[2:3]
	v_cvt_pk_bf16_f32 v76, v232, v233
	v_cvt_pk_bf16_f32 v77, v234, v235
	v_cvt_pk_bf16_f32 v78, v236, v237
	v_cvt_pk_bf16_f32 v79, v238, v239
	s_mov_b64 vcc, s[64:65]
	s_nop 0
	v_cndmask_b32_dpp v136, v132, v128, vcc quad_perm:[1,0,3,2] row_mask:0xf bank_mask:0xf
	v_cndmask_b32_dpp v137, v133, v129, vcc quad_perm:[1,0,3,2] row_mask:0xf bank_mask:0xf
	v_cndmask_b32_dpp v138, v134, v130, vcc quad_perm:[1,0,3,2] row_mask:0xf bank_mask:0xf
	v_cndmask_b32_dpp v139, v135, v131, vcc quad_perm:[1,0,3,2] row_mask:0xf bank_mask:0xf
	s_mov_b64 vcc, s[66:67]
	v_cndmask_b32_dpp v140, v128, v132, vcc quad_perm:[1,0,3,2] row_mask:0xf bank_mask:0xf
	v_cndmask_b32_dpp v141, v129, v133, vcc quad_perm:[1,0,3,2] row_mask:0xf bank_mask:0xf
	v_cndmask_b32_dpp v142, v130, v134, vcc quad_perm:[1,0,3,2] row_mask:0xf bank_mask:0xf
	v_cndmask_b32_dpp v143, v131, v135, vcc quad_perm:[1,0,3,2] row_mask:0xf bank_mask:0xf
	global_store_dwordx4 v[86:87], v[136:139], off
	global_store_dwordx4 v[86:87], v[140:143], off offset:2048
	s_mov_b64 vcc, s[64:65]
	s_nop 0
	v_cndmask_b32_dpp v136, v76, v112, vcc quad_perm:[1,0,3,2] row_mask:0xf bank_mask:0xf
	v_cndmask_b32_dpp v137, v77, v113, vcc quad_perm:[1,0,3,2] row_mask:0xf bank_mask:0xf
	v_cndmask_b32_dpp v138, v78, v114, vcc quad_perm:[1,0,3,2] row_mask:0xf bank_mask:0xf
	v_cndmask_b32_dpp v139, v79, v115, vcc quad_perm:[1,0,3,2] row_mask:0xf bank_mask:0xf
	s_mov_b64 vcc, s[66:67]
	v_cndmask_b32_dpp v140, v112, v76, vcc quad_perm:[1,0,3,2] row_mask:0xf bank_mask:0xf
	v_cndmask_b32_dpp v141, v113, v77, vcc quad_perm:[1,0,3,2] row_mask:0xf bank_mask:0xf
	v_cndmask_b32_dpp v142, v114, v78, vcc quad_perm:[1,0,3,2] row_mask:0xf bank_mask:0xf
	v_cndmask_b32_dpp v143, v115, v79, vcc quad_perm:[1,0,3,2] row_mask:0xf bank_mask:0xf
	global_store_dwordx4 v[116:117], v[136:139], off
	global_store_dwordx4 v[116:117], v[140:143], off offset:2048
	v_lshl_add_u64 v[86:87], v[86:87], 0, s[70:71]
	v_lshl_add_u64 v[116:117], v[116:117], 0, s[70:71]
	v_mov_b32_e32 v74, v68
	v_cvt_pk_bf16_f32 v128, v168, v169
	v_cvt_pk_bf16_f32 v129, v160, v161
	v_cvt_pk_bf16_f32 v130, v180, v181
	v_cvt_pk_bf16_f32 v131, v176, v177
	v_cvt_pk_bf16_f32 v132, v146, v147
	v_cvt_pk_bf16_f32 v133, v144, v145
	v_cvt_pk_bf16_f32 v134, v150, v151
	v_cvt_pk_bf16_f32 v135, v148, v149
	v_pk_mul_f32 v[232:233], v[168:169], v[74:75] op_sel_hi:[1,0]
	v_pk_mul_f32 v[234:235], v[160:161], v[74:75] op_sel_hi:[1,0]
	v_pk_mul_f32 v[236:237], v[180:181], v[74:75] op_sel_hi:[1,0]
	v_pk_mul_f32 v[238:239], v[176:177], v[74:75] op_sel_hi:[1,0]
	v_pk_fma_f32 v[232:233], v[16:17], v[232:233], v[12:13]
	v_pk_fma_f32 v[234:235], v[18:19], v[234:235], v[14:15]
	v_pk_fma_f32 v[236:237], v[20:21], v[236:237], v[8:9]
	v_pk_fma_f32 v[238:239], v[22:23], v[238:239], v[10:11]
	v_cvt_pk_bf16_f32 v112, v232, v233
	v_cvt_pk_bf16_f32 v113, v234, v235
	v_cvt_pk_bf16_f32 v114, v236, v237
	v_cvt_pk_bf16_f32 v115, v238, v239
	v_pk_mul_f32 v[232:233], v[146:147], v[74:75] op_sel_hi:[1,0]
	v_pk_mul_f32 v[234:235], v[144:145], v[74:75] op_sel_hi:[1,0]
	v_pk_mul_f32 v[236:237], v[150:151], v[74:75] op_sel_hi:[1,0]
	v_pk_mul_f32 v[238:239], v[148:149], v[74:75] op_sel_hi:[1,0]
	v_pk_fma_f32 v[232:233], v[32:33], v[232:233], v[4:5]
	v_pk_fma_f32 v[234:235], v[34:35], v[234:235], v[6:7]
	v_pk_fma_f32 v[236:237], v[36:37], v[236:237], v[0:1]
	v_pk_fma_f32 v[238:239], v[38:39], v[238:239], v[2:3]
	v_cvt_pk_bf16_f32 v76, v232, v233
	v_cvt_pk_bf16_f32 v77, v234, v235
	v_cvt_pk_bf16_f32 v78, v236, v237
	v_cvt_pk_bf16_f32 v79, v238, v239
	s_mov_b64 vcc, s[64:65]
	s_nop 0
	v_cndmask_b32_dpp v136, v132, v128, vcc quad_perm:[1,0,3,2] row_mask:0xf bank_mask:0xf
	v_cndmask_b32_dpp v137, v133, v129, vcc quad_perm:[1,0,3,2] row_mask:0xf bank_mask:0xf
	v_cndmask_b32_dpp v138, v134, v130, vcc quad_perm:[1,0,3,2] row_mask:0xf bank_mask:0xf
	v_cndmask_b32_dpp v139, v135, v131, vcc quad_perm:[1,0,3,2] row_mask:0xf bank_mask:0xf
	s_mov_b64 vcc, s[66:67]
	v_cndmask_b32_dpp v140, v128, v132, vcc quad_perm:[1,0,3,2] row_mask:0xf bank_mask:0xf
	v_cndmask_b32_dpp v141, v129, v133, vcc quad_perm:[1,0,3,2] row_mask:0xf bank_mask:0xf
	v_cndmask_b32_dpp v142, v130, v134, vcc quad_perm:[1,0,3,2] row_mask:0xf bank_mask:0xf
	v_cndmask_b32_dpp v143, v131, v135, vcc quad_perm:[1,0,3,2] row_mask:0xf bank_mask:0xf
	global_store_dwordx4 v[86:87], v[136:139], off
	global_store_dwordx4 v[86:87], v[140:143], off offset:2048
	s_mov_b64 vcc, s[64:65]
	s_nop 0
	v_cndmask_b32_dpp v136, v76, v112, vcc quad_perm:[1,0,3,2] row_mask:0xf bank_mask:0xf
	v_cndmask_b32_dpp v137, v77, v113, vcc quad_perm:[1,0,3,2] row_mask:0xf bank_mask:0xf
	v_cndmask_b32_dpp v138, v78, v114, vcc quad_perm:[1,0,3,2] row_mask:0xf bank_mask:0xf
	v_cndmask_b32_dpp v139, v79, v115, vcc quad_perm:[1,0,3,2] row_mask:0xf bank_mask:0xf
	s_mov_b64 vcc, s[66:67]
	v_cndmask_b32_dpp v140, v112, v76, vcc quad_perm:[1,0,3,2] row_mask:0xf bank_mask:0xf
	v_cndmask_b32_dpp v141, v113, v77, vcc quad_perm:[1,0,3,2] row_mask:0xf bank_mask:0xf
	v_cndmask_b32_dpp v142, v114, v78, vcc quad_perm:[1,0,3,2] row_mask:0xf bank_mask:0xf
	v_cndmask_b32_dpp v143, v115, v79, vcc quad_perm:[1,0,3,2] row_mask:0xf bank_mask:0xf
	global_store_dwordx4 v[116:117], v[136:139], off
	global_store_dwordx4 v[116:117], v[140:143], off offset:2048
	v_lshl_add_u64 v[86:87], v[86:87], 0, s[68:69]
	v_lshl_add_u64 v[116:117], v[116:117], 0, s[68:69]
; __device__ __forceinline__ unsigned cvt_pk_bf16(float lo, float hi) { unsigned r; asm("v_cvt_pk_bf16_f32 %0, %1, %2" : "=v"(r) : "v"(lo), "v"(hi)); return r; }
; __device__ __forceinline__ void st_bf16x8(bf16_t* p, const f32x4 a, const f32x4 b) { uint4 o; o.x = cvt_pk_bf16(a[0], a[1]); o.y = cvt_pk_bf16(a[2], a[3]); o.z = cvt_pk_bf16(b[0], b[1]); o.w = cvt_pk_bf16(b[2], b[3]); *(uint4*)p = o; }
;     __device__ __forceinline__ void fused(f32x4 (&acc)[2][2][4][2], const Unit& u, int wr, int wc, int fr, int fq, float* smem) const {
;     ...
; #pragma unroll
;         for (int ai = 0; ai < 2; ++ai)
; #pragma unroll
;             for (int m = 0; m < 4; ++m) { const int rl = rl0 + ai * HALF + m * 16; const size_t ro = (size_t)(u.pm * BM + rl) * DM; const float r = rsv[rl];
; #pragma unroll
;                 for (int bj = 0; bj < 2; ++bj) { const int c = cb + bj * HALF; const f32x4 v0 = acc[ai][bj][m][0], v1 = acc[ai][bj][m][1];
;                     if (MODE == 0) { st_bf16x8(X1 + ro + c, v0, v1); st_bf16x8(H + ro + c, v0 * r * gs[bj][0] + sh[bj][0], v1 * r * gs[bj][1] + sh[bj][1]); }
;                     else { *(f32x4*)(out + ro + c) = v0 * r * gs[bj][0]; *(f32x4*)(out + ro + c + 4) = v1 * r * gs[bj][1]; } } }
	v_mov_b32_e32 v74, v69
	v_cvt_pk_bf16_f32 v128, v108, v109
	v_cvt_pk_bf16_f32 v129, v110, v111
	v_cvt_pk_bf16_f32 v130, v104, v105
	v_cvt_pk_bf16_f32 v131, v106, v107
	v_cvt_pk_bf16_f32 v132, v100, v101
	v_cvt_pk_bf16_f32 v133, v102, v103
	v_cvt_pk_bf16_f32 v134, v96, v97
	v_cvt_pk_bf16_f32 v135, v98, v99
	v_pk_mul_f32 v[232:233], v[108:109], v[74:75] op_sel_hi:[1,0]
	v_pk_mul_f32 v[234:235], v[110:111], v[74:75] op_sel_hi:[1,0]
	v_pk_mul_f32 v[236:237], v[104:105], v[74:75] op_sel_hi:[1,0]
	v_pk_mul_f32 v[238:239], v[106:107], v[74:75] op_sel_hi:[1,0]
	v_pk_fma_f32 v[232:233], v[16:17], v[232:233], v[12:13]
	v_pk_fma_f32 v[234:235], v[18:19], v[234:235], v[14:15]
	v_pk_fma_f32 v[236:237], v[20:21], v[236:237], v[8:9]
	v_pk_fma_f32 v[238:239], v[22:23], v[238:239], v[10:11]
	v_cvt_pk_bf16_f32 v112, v232, v233
	v_cvt_pk_bf16_f32 v113, v234, v235
	v_cvt_pk_bf16_f32 v114, v236, v237
	v_cvt_pk_bf16_f32 v115, v238, v239
	v_pk_mul_f32 v[232:233], v[100:101], v[74:75] op_sel_hi:[1,0]
	v_pk_mul_f32 v[234:235], v[102:103], v[74:75] op_sel_hi:[1,0]
	v_pk_mul_f32 v[236:237], v[96:97], v[74:75] op_sel_hi:[1,0]
	v_pk_mul_f32 v[238:239], v[98:99], v[74:75] op_sel_hi:[1,0]
	v_pk_fma_f32 v[232:233], v[32:33], v[232:233], v[4:5]
	v_pk_fma_f32 v[234:235], v[34:35], v[234:235], v[6:7]
	v_pk_fma_f32 v[236:237], v[36:37], v[236:237], v[0:1]
	v_pk_fma_f32 v[238:239], v[38:39], v[238:239], v[2:3]
	v_cvt_pk_bf16_f32 v76, v232, v233
	v_cvt_pk_bf16_f32 v77, v234, v235
	v_cvt_pk_bf16_f32 v78, v236, v237
	v_cvt_pk_bf16_f32 v79, v238, v239
	s_mov_b64 vcc, s[64:65]
	s_nop 0
	v_cndmask_b32_dpp v136, v132, v128, vcc quad_perm:[1,0,3,2] row_mask:0xf bank_mask:0xf
	v_cndmask_b32_dpp v137, v133, v129, vcc quad_perm:[1,0,3,2] row_mask:0xf bank_mask:0xf
	v_cndmask_b32_dpp v138, v134, v130, vcc quad_perm:[1,0,3,2] row_mask:0xf bank_mask:0xf
	v_cndmask_b32_dpp v139, v135, v131, vcc quad_perm:[1,0,3,2] row_mask:0xf bank_mask:0xf
	s_mov_b64 vcc, s[66:67]
	v_cndmask_b32_dpp v140, v128, v132, vcc quad_perm:[1,0,3,2] row_mask:0xf bank_mask:0xf
	v_cndmask_b32_dpp v141, v129, v133, vcc quad_perm:[1,0,3,2] row_mask:0xf bank_mask:0xf
	v_cndmask_b32_dpp v142, v130, v134, vcc quad_perm:[1,0,3,2] row_mask:0xf bank_mask:0xf
	v_cndmask_b32_dpp v143, v131, v135, vcc quad_perm:[1,0,3,2] row_mask:0xf bank_mask:0xf
	global_store_dwordx4 v[86:87], v[136:139], off
	global_store_dwordx4 v[86:87], v[140:143], off offset:2048
	s_mov_b64 vcc, s[64:65]
	s_nop 0
	v_cndmask_b32_dpp v136, v76, v112, vcc quad_perm:[1,0,3,2] row_mask:0xf bank_mask:0xf
	v_cndmask_b32_dpp v137, v77, v113, vcc quad_perm:[1,0,3,2] row_mask:0xf bank_mask:0xf
	v_cndmask_b32_dpp v138, v78, v114, vcc quad_perm:[1,0,3,2] row_mask:0xf bank_mask:0xf
	v_cndmask_b32_dpp v139, v79, v115, vcc quad_perm:[1,0,3,2] row_mask:0xf bank_mask:0xf
	s_mov_b64 vcc, s[66:67]
	v_cndmask_b32_dpp v140, v112, v76, vcc quad_perm:[1,0,3,2] row_mask:0xf bank_mask:0xf
	v_cndmask_b32_dpp v141, v113, v77, vcc quad_perm:[1,0,3,2] row_mask:0xf bank_mask:0xf
	v_cndmask_b32_dpp v142, v114, v78, vcc quad_perm:[1,0,3,2] row_mask:0xf bank_mask:0xf
	v_cndmask_b32_dpp v143, v115, v79, vcc quad_perm:[1,0,3,2] row_mask:0xf bank_mask:0xf
	global_store_dwordx4 v[116:117], v[136:139], off
	global_store_dwordx4 v[116:117], v[140:143], off offset:2048
	v_lshl_add_u64 v[86:87], v[86:87], 0, s[68:69]
	v_lshl_add_u64 v[116:117], v[116:117], 0, s[68:69]
	v_mov_b32_e32 v74, v70
	v_cvt_pk_bf16_f32 v128, v92, v93
	v_cvt_pk_bf16_f32 v129, v94, v95
	v_cvt_pk_bf16_f32 v130, v88, v89
	v_cvt_pk_bf16_f32 v131, v90, v91
	v_cvt_pk_bf16_f32 v132, v84, v85
	v_cvt_pk_bf16_f32 v133, v62, v63
	v_cvt_pk_bf16_f32 v134, v80, v81
	v_cvt_pk_bf16_f32 v135, v82, v83
	v_pk_mul_f32 v[232:233], v[92:93], v[74:75] op_sel_hi:[1,0]
	v_pk_mul_f32 v[234:235], v[94:95], v[74:75] op_sel_hi:[1,0]
	v_pk_mul_f32 v[236:237], v[88:89], v[74:75] op_sel_hi:[1,0]
	v_pk_mul_f32 v[238:239], v[90:91], v[74:75] op_sel_hi:[1,0]
	v_pk_fma_f32 v[232:233], v[16:17], v[232:233], v[12:13]
	v_pk_fma_f32 v[234:235], v[18:19], v[234:235], v[14:15]
	v_pk_fma_f32 v[236:237], v[20:21], v[236:237], v[8:9]
	v_pk_fma_f32 v[238:239], v[22:23], v[238:239], v[10:11]
	v_cvt_pk_bf16_f32 v112, v232, v233
	v_cvt_pk_bf16_f32 v113, v234, v235
	v_cvt_pk_bf16_f32 v114, v236, v237
	v_cvt_pk_bf16_f32 v115, v238, v239
	v_pk_mul_f32 v[232:233], v[84:85], v[74:75] op_sel_hi:[1,0]
	v_pk_mul_f32 v[234:235], v[62:63], v[74:75] op_sel_hi:[1,0]
	v_pk_mul_f32 v[236:237], v[80:81], v[74:75] op_sel_hi:[1,0]
	v_pk_mul_f32 v[238:239], v[82:83], v[74:75] op_sel_hi:[1,0]
	v_pk_fma_f32 v[232:233], v[32:33], v[232:233], v[4:5]
	v_pk_fma_f32 v[234:235], v[34:35], v[234:235], v[6:7]
	v_pk_fma_f32 v[236:237], v[36:37], v[236:237], v[0:1]
	v_pk_fma_f32 v[238:239], v[38:39], v[238:239], v[2:3]
	v_cvt_pk_bf16_f32 v76, v232, v233
	v_cvt_pk_bf16_f32 v77, v234, v235
	v_cvt_pk_bf16_f32 v78, v236, v237
	v_cvt_pk_bf16_f32 v79, v238, v239
	s_mov_b64 vcc, s[64:65]
	s_nop 0
	v_cndmask_b32_dpp v136, v132, v128, vcc quad_perm:[1,0,3,2] row_mask:0xf bank_mask:0xf
; __device__ __forceinline__ void st_bf16x8(bf16_t* p, const f32x4 a, const f32x4 b) { uint4 o; o.x = cvt_pk_bf16(a[0], a[1]); o.y = cvt_pk_bf16(a[2], a[3]); o.z = cvt_pk_bf16(b[0], b[1]); o.w = cvt_pk_bf16(b[2], b[3]); *(uint4*)p = o; }
;     __device__ __forceinline__ void fused(f32x4 (&acc)[2][2][4][2], const Unit& u, int wr, int wc, int fr, int fq, float* smem) const {
;     ...
; #pragma unroll
;         for (int ai = 0; ai < 2; ++ai)
; #pragma unroll
;             for (int m = 0; m < 4; ++m) { const int rl = rl0 + ai * HALF + m * 16; const size_t ro = (size_t)(u.pm * BM + rl) * DM; const float r = rsv[rl];
; #pragma unroll
;                 for (int bj = 0; bj < 2; ++bj) { const int c = cb + bj * HALF; const f32x4 v0 = acc[ai][bj][m][0], v1 = acc[ai][bj][m][1];
;                     if (MODE == 0) { st_bf16x8(X1 + ro + c, v0, v1); st_bf16x8(H + ro + c, v0 * r * gs[bj][0] + sh[bj][0], v1 * r * gs[bj][1] + sh[bj][1]); }
;                     else { *(f32x4*)(out + ro + c) = v0 * r * gs[bj][0]; *(f32x4*)(out + ro + c + 4) = v1 * r * gs[bj][1]; } } }
;         __syncthreads();
	v_cndmask_b32_dpp v137, v133, v129, vcc quad_perm:[1,0,3,2] row_mask:0xf bank_mask:0xf
	v_cndmask_b32_dpp v138, v134, v130, vcc quad_perm:[1,0,3,2] row_mask:0xf bank_mask:0xf
	v_cndmask_b32_dpp v139, v135, v131, vcc quad_perm:[1,0,3,2] row_mask:0xf bank_mask:0xf
	s_mov_b64 vcc, s[66:67]
	v_cndmask_b32_dpp v140, v128, v132, vcc quad_perm:[1,0,3,2] row_mask:0xf bank_mask:0xf
	v_cndmask_b32_dpp v141, v129, v133, vcc quad_perm:[1,0,3,2] row_mask:0xf bank_mask:0xf
	v_cndmask_b32_dpp v142, v130, v134, vcc quad_perm:[1,0,3,2] row_mask:0xf bank_mask:0xf
	v_cndmask_b32_dpp v143, v131, v135, vcc quad_perm:[1,0,3,2] row_mask:0xf bank_mask:0xf
	global_store_dwordx4 v[86:87], v[136:139], off
	global_store_dwordx4 v[86:87], v[140:143], off offset:2048
	s_mov_b64 vcc, s[64:65]
	s_nop 0
	v_cndmask_b32_dpp v136, v76, v112, vcc quad_perm:[1,0,3,2] row_mask:0xf bank_mask:0xf
	v_cndmask_b32_dpp v137, v77, v113, vcc quad_perm:[1,0,3,2] row_mask:0xf bank_mask:0xf
	v_cndmask_b32_dpp v138, v78, v114, vcc quad_perm:[1,0,3,2] row_mask:0xf bank_mask:0xf
	v_cndmask_b32_dpp v139, v79, v115, vcc quad_perm:[1,0,3,2] row_mask:0xf bank_mask:0xf
	s_mov_b64 vcc, s[66:67]
	v_cndmask_b32_dpp v140, v112, v76, vcc quad_perm:[1,0,3,2] row_mask:0xf bank_mask:0xf
	v_cndmask_b32_dpp v141, v113, v77, vcc quad_perm:[1,0,3,2] row_mask:0xf bank_mask:0xf
	v_cndmask_b32_dpp v142, v114, v78, vcc quad_perm:[1,0,3,2] row_mask:0xf bank_mask:0xf
	v_cndmask_b32_dpp v143, v115, v79, vcc quad_perm:[1,0,3,2] row_mask:0xf bank_mask:0xf
	global_store_dwordx4 v[116:117], v[136:139], off
	global_store_dwordx4 v[116:117], v[140:143], off offset:2048
	v_lshl_add_u64 v[86:87], v[86:87], 0, s[68:69]
	v_lshl_add_u64 v[116:117], v[116:117], 0, s[68:69]
	v_mov_b32_e32 v74, v71
	v_cvt_pk_bf16_f32 v128, v58, v59
	v_cvt_pk_bf16_f32 v129, v56, v57
	v_cvt_pk_bf16_f32 v130, v72, v73
	v_cvt_pk_bf16_f32 v131, v60, v61
	v_cvt_pk_bf16_f32 v132, v50, v51
	v_cvt_pk_bf16_f32 v133, v48, v49
	v_cvt_pk_bf16_f32 v134, v54, v55
	v_cvt_pk_bf16_f32 v135, v52, v53
	v_pk_mul_f32 v[232:233], v[58:59], v[74:75] op_sel_hi:[1,0]
	v_pk_mul_f32 v[234:235], v[56:57], v[74:75] op_sel_hi:[1,0]
	v_pk_mul_f32 v[236:237], v[72:73], v[74:75] op_sel_hi:[1,0]
	v_pk_mul_f32 v[238:239], v[60:61], v[74:75] op_sel_hi:[1,0]
	v_pk_fma_f32 v[232:233], v[16:17], v[232:233], v[12:13]
	v_pk_fma_f32 v[234:235], v[18:19], v[234:235], v[14:15]
	v_pk_fma_f32 v[236:237], v[20:21], v[236:237], v[8:9]
	v_pk_fma_f32 v[238:239], v[22:23], v[238:239], v[10:11]
	v_cvt_pk_bf16_f32 v112, v232, v233
	v_cvt_pk_bf16_f32 v113, v234, v235
	v_cvt_pk_bf16_f32 v114, v236, v237
	v_cvt_pk_bf16_f32 v115, v238, v239
	v_pk_mul_f32 v[232:233], v[50:51], v[74:75] op_sel_hi:[1,0]
	v_pk_mul_f32 v[234:235], v[48:49], v[74:75] op_sel_hi:[1,0]
	v_pk_mul_f32 v[236:237], v[54:55], v[74:75] op_sel_hi:[1,0]
	v_pk_mul_f32 v[238:239], v[52:53], v[74:75] op_sel_hi:[1,0]
	v_pk_fma_f32 v[232:233], v[32:33], v[232:233], v[4:5]
	v_pk_fma_f32 v[234:235], v[34:35], v[234:235], v[6:7]
	v_pk_fma_f32 v[236:237], v[36:37], v[236:237], v[0:1]
	v_pk_fma_f32 v[238:239], v[38:39], v[238:239], v[2:3]
	v_cvt_pk_bf16_f32 v76, v232, v233
	v_cvt_pk_bf16_f32 v77, v234, v235
	v_cvt_pk_bf16_f32 v78, v236, v237
	v_cvt_pk_bf16_f32 v79, v238, v239
	s_mov_b64 vcc, s[64:65]
	s_nop 0
	v_cndmask_b32_dpp v136, v132, v128, vcc quad_perm:[1,0,3,2] row_mask:0xf bank_mask:0xf
	v_cndmask_b32_dpp v137, v133, v129, vcc quad_perm:[1,0,3,2] row_mask:0xf bank_mask:0xf
	v_cndmask_b32_dpp v138, v134, v130, vcc quad_perm:[1,0,3,2] row_mask:0xf bank_mask:0xf
	v_cndmask_b32_dpp v139, v135, v131, vcc quad_perm:[1,0,3,2] row_mask:0xf bank_mask:0xf
	s_mov_b64 vcc, s[66:67]
	v_cndmask_b32_dpp v140, v128, v132, vcc quad_perm:[1,0,3,2] row_mask:0xf bank_mask:0xf
	v_cndmask_b32_dpp v141, v129, v133, vcc quad_perm:[1,0,3,2] row_mask:0xf bank_mask:0xf
	v_cndmask_b32_dpp v142, v130, v134, vcc quad_perm:[1,0,3,2] row_mask:0xf bank_mask:0xf
	v_cndmask_b32_dpp v143, v131, v135, vcc quad_perm:[1,0,3,2] row_mask:0xf bank_mask:0xf
	global_store_dwordx4 v[86:87], v[136:139], off
	global_store_dwordx4 v[86:87], v[140:143], off offset:2048
	s_mov_b64 vcc, s[64:65]
	s_nop 0
	v_cndmask_b32_dpp v136, v76, v112, vcc quad_perm:[1,0,3,2] row_mask:0xf bank_mask:0xf
	v_cndmask_b32_dpp v137, v77, v113, vcc quad_perm:[1,0,3,2] row_mask:0xf bank_mask:0xf
	v_cndmask_b32_dpp v138, v78, v114, vcc quad_perm:[1,0,3,2] row_mask:0xf bank_mask:0xf
	v_cndmask_b32_dpp v139, v79, v115, vcc quad_perm:[1,0,3,2] row_mask:0xf bank_mask:0xf
	s_mov_b64 vcc, s[66:67]
	v_cndmask_b32_dpp v140, v112, v76, vcc quad_perm:[1,0,3,2] row_mask:0xf bank_mask:0xf
	v_cndmask_b32_dpp v141, v113, v77, vcc quad_perm:[1,0,3,2] row_mask:0xf bank_mask:0xf
	v_cndmask_b32_dpp v142, v114, v78, vcc quad_perm:[1,0,3,2] row_mask:0xf bank_mask:0xf
	v_cndmask_b32_dpp v143, v115, v79, vcc quad_perm:[1,0,3,2] row_mask:0xf bank_mask:0xf
	global_store_dwordx4 v[116:117], v[136:139], off
	global_store_dwordx4 v[116:117], v[140:143], off offset:2048
	s_barrier

; __device__ __forceinline__ void st_wt_f32x4(float* p, const f32x4 v) { asm volatile("global_store_dwordx4 %0, %1, off sc1\n\ts_nop 1" :: "v"(p), "v"(v) : "memory"); }
;     __device__ __forceinline__ void frag(const f32x4 a, int row, int c) const { if (row < NB) *(f32x4*)(mod + (size_t)row * NMOD + c) = a + *(const f32x4*)(b_ada + c); }
;     __device__ __forceinline__ void frag(const f32x4 a, int row, int cs) const {
;         const int c = (cs & ~31) + perm32(cs & 31);
;         const float* gt = mod + (size_t)batch_of(row) * NMOD + gate_off; float* orow = out + (size_t)row * DM;
;         const float* br = inplace ? orow : (row < NP ? xp + (size_t)row * DM : xs + (size_t)(row - NP) * DM);
;         const f32x4 r = *(const f32x4*)(br + c) + *(const f32x4*)(gt + c) * a;
;         if (inplace) st_wt_f32x4(orow + c, r); else *(f32x4*)(orow + c) = r; }
.LBB0_579:
	s_or_b64 exec, exec, s[6:7]
	s_and_b64 s[6:7], vcc, s[0:1]
	s_and_saveexec_b64 s[0:1], s[6:7]
	s_cbranch_execz .LBB0_574
	v_lshlrev_b32_e32 v1, 4, v14
	v_add_u32_e32 v9, 0x4000, v1
	v_lshlrev_b32_e32 v14, 4, v13
	v_lshlrev_b32_e32 v13, 2, v13
	v_or_b32_e32 v15, v9, v10
	v_and_b32_e32 v13, 4, v13
	v_and_b32_e32 v14, 0xffffffe0, v14
	v_and_b32_e32 v16, 0x60, v14
	v_bfe_u32 v17, v14, 7, 1
	v_and_b32_e32 v14, 0xffffff00, v14
	v_lshl_or_b32 v14, v16, 1, v14
	v_lshl_or_b32 v14, v17, 5, v14
	v_or3_b32 v14, v14, v13, v6
	v_lshrrev_b32_e32 v9, 11, v9
	v_add_u32_e32 v13, 0xffffc008, v15
	v_cmp_lt_u32_e32 vcc, s9, v1
	v_mov_b64_e32 v[16:17], s[16:17]
	v_add_u32_e32 v20, 0xffffc000, v15
	v_cndmask_b32_e32 v1, v13, v9, vcc
	v_mad_u64_u32 v[18:19], s[6:7], v1, s12, v[16:17]
	v_lshlrev_b32_e32 v16, 10, v15
	v_mov_b32_e32 v17, v0
	v_mov_b32_e32 v21, v0
	v_ashrrev_i32_e32 v15, 31, v14
	v_lshlrev_b64 v[22:23], 2, v[16:17]
	v_lshlrev_b64 v[20:21], 12, v[20:21]
	v_lshlrev_b64 v[24:25], 2, v[14:15]
	v_lshl_add_u64 v[16:17], s[36:37], 0, v[22:23]
	v_lshl_add_u64 v[20:21], s[38:39], 0, v[20:21]
	v_lshl_add_u64 v[18:19], v[18:19], 0, v[24:25]
	v_cndmask_b32_e32 v17, v21, v17, vcc
	v_cndmask_b32_e32 v16, v20, v16, vcc
	v_add_co_u32_e32 v18, vcc, s13, v18
	v_lshl_add_u64 v[14:15], v[16:17], 0, v[24:25]
	s_nop 0
	v_addc_co_u32_e32 v19, vcc, 0, v19, vcc
	global_load_dwordx4 v[14:17], v[14:15], off
	v_lshl_add_u64 v[22:23], s[56:57], 0, v[22:23]
	global_load_dwordx4 v[18:21], v[18:19], off
	s_waitcnt vmcnt(0)
	v_pk_fma_f32 v[4:5], v[4:5], v[20:21], v[16:17]
	v_pk_fma_f32 v[2:3], v[2:3], v[18:19], v[14:15]
	v_lshl_add_u64 v[14:15], v[22:23], 0, v[24:25]
	global_store_dwordx4 v[14:15], v[2:5], off
	s_branch .LBB0_574
